# dilated-window attention: band mask folded into a padded LDS bias table (out-of-band entries hold -1e30), paired LDS reads + one FMA per score
# speedup vs baseline: 1.0540x; 1.0113x over previous
; template <int DQK, int DV, int MODE> ...
;     ...
;       *(bf16x8*)(Qs + (qi * NKS + ks) * 512) = *(const bf16x8*)(Qp + (unsigned)((w * 32 + qi * 16 + fr) * qrs + ks * 32 + fq * 8));
; #pragma unroll
;   for (int qi = 0; qi < 2; ++qi) {
;     mrow[qi] = -1e30f; lrow[qi] = 0.f;
; #pragma unroll
;     for (int dt = 0; dt < NDT; ++dt) O[qi][dt] = (f32x4){0.f, 0.f, 0.f, 0.f};
;   }
;   int wkb, wke;
;   if (MODE == 0) { wkb = max(kt_begin, w >> 1); wke = (w * 32 + 159) / 64 + 1; }
;   else { wkb = 0; wke = (qpos0 + w * 32 + 31) / 64 + 1; }
;   u32x4 rk[NKC], rv[NVC];
;   auto gload = [&](int kt) {
; #pragma unroll
;     for (int i = 0; i < NKC; ++i) { const int c = tid + 256 * i, key = c / KCH, part = c % KCH; rk[i] = *(const u32x4*)(Kp + (unsigned)((kt * 64 + key) * krs + part * 8)); }
;     if (MODE == 0) {
; #pragma unroll
;       for (int i = 0; i < NVC; ++i) { const int c = tid + 256 * i, key = c >> 3, part = c & 7; rv[i] = *(const u32x4*)(Vp + (unsigned)((kt * 64 + key) * vrs + part * 8)); }
;     } else {
; #pragma unroll
;       for (int i = 0; i < NVC; ++i) { const int c = tid + 256 * i, dv = c >> 3, kc = c & 7; rv[i] = *(const u32x4*)(Vp + (unsigned)(dv * vrs + kt * 64 + kc * 8)); }
;     }
;   };
;   auto sstore = [&]() {
; #pragma unroll
;     for (int i = 0; i < NKC; ++i) { const int c = tid + 256 * i, key = c / KCH, part = c % KCH; *(u32x4*)(Ks + key * KST + part * 8) = rk[i]; }
;     if (MODE == 0) {
; #pragma unroll
;       for (int i = 0; i < NVC; ++i) {
;         const int c = tid + 256 * i, key = c >> 3, part = c & 7;
;         const int pos = (key & 32) + ((key >> 2) & 3) * 8 + ((key >> 4) & 1) * 4 + (key & 3);
; #pragma unroll
;     ...
;     const int g = a / 768, rem = a % 768, b = rem / 384, h = (rem >> 6) % 6, blk = rem & 63;
;     const int d = g == 0 ? 1 : (g == 1 ? 4 : 16);
;     const int r = blk % d, n = blk / d;
;     for (int i = tid; i < 129; i += NTHREADS) bias_lds[i] = p.biasA2[(g * 6 + h) * 129 + i];
;     const long row_q0 = (long)b * SEQ + (long)n * 128 * d + r;
;     const long row_k0 = row_q0 - 128L * d;
;     f32x4 O[2][4]; float mr[2], lr[2];
;     flash_block<64, 64, 0>(p.qkvA + row_q0 * 1152 + h * 64, 1152 * d, p.qkvA + row_k0 * 1152 + 384 + h * 64, 1152 * d,
;                            p.qkvA + row_k0 * 1152 + 768 + h * 64, 1152 * d, n == 0 ? 2 : 0, 4, 0, n == 0 ? 128 : 0, 0.125f * LOG2E, smem, O, mr, lr, tid);
.LBB0_599:
	s_or_b64 exec, exec, s[2:3]
	v_mov_b32_e32 v156, 0xf149f2ca
	v_lshlrev_b32_e32 v157, 2, v122
	v_cmp_gt_u32_e32 vcc, 0x7f, v122
	v_add_u32_e32 v158, 0x8604, v157
	v_add_u32_e32 v159, 0x8808, v157
	s_nop 0
	v_cndmask_b32_e32 v158, v159, v158, vcc
	ds_write_b32 v158, v156
	s_mul_i32 s2, s1, 0x2aab
	s_lshr_b32 s3, s2, 31
	s_ashr_i32 s2, s2, 22
	s_add_i32 s2, s2, s3
	s_and_b32 s1, s1, 63
	s_add_i32 s3, s12, 0x2ff
	s_addk_i32 s12, 0xfd00
	s_cmpk_lt_u32 s12, 0x300
	s_cselect_b64 s[4:5], -1, 0
	v_writelane_b32 v254, s4, 57
	v_readlane_b32 s12, v252, 25
	v_readlane_b32 s16, v252, 29
	v_writelane_b32 v254, s5, 58
	s_and_b64 s[4:5], s[4:5], exec
	s_movk_i32 s4, 0x1200
	s_cselect_b32 s6, 4, 16
	s_cselect_b32 s7, 2, 4
	s_cselect_b32 s8, s4, 0x4800
	s_cmpk_lt_u32 s3, 0x5ff
	s_cselect_b64 s[4:5], -1, 0
	v_writelane_b32 v254, s4, 59
	v_readlane_b32 s17, v252, 30
	v_mov_b32_e32 v117, 0
	v_writelane_b32 v254, s5, 60
	s_and_b64 s[4:5], s[4:5], exec
	s_cselect_b32 s4, 1, s6
	s_cselect_b32 s5, 0, s7
	s_cselect_b32 s6, 0x480, s8
	s_add_i32 s3, s4, -1
	s_lshr_b32 s8, s1, s5
	s_and_b32 s7, s3, s1
	s_bfe_i64 s[2:3], s[2:3], 0x100000
	s_lshl_b32 s1, s8, 7
	s_lshl_b64 s[2:3], s[2:3], 13
	s_lshl_b32 s1, s1, s5
	s_add_u32 s1, s2, s1
	s_addc_u32 s2, s3, 0
	s_or_b32 s3, s1, s7
	s_lshl_b32 s1, s4, 7
	s_sub_u32 s4, s3, s1
	s_subb_u32 s5, s2, 0
	v_writelane_b32 v254, s2, 61
	s_mul_i32 s1, s2, 0x900
	s_mul_hi_u32 s2, s3, 0x900
	s_add_i32 s2, s2, s1
	s_mul_i32 s1, s3, 0x900
	v_writelane_b32 v254, s3, 62
	s_add_u32 s3, s16, s1
	s_addc_u32 s7, s17, s2
	s_lshl_b32 s0, s0, 6
	s_ashr_i32 s1, s0, 31
	v_writelane_b32 v254, s0, 63
	s_mulk_i32 s5, 0x900
	v_mul_lo_u32 v10, s6, v134
	v_writelane_b32 v255, s1, 0
	s_lshl_b64 s[0:1], s[0:1], 1
	s_add_u32 s2, s3, s0
	s_addc_u32 s3, s7, s1
	s_mul_hi_u32 s7, s4, 0x900
	s_add_i32 s7, s7, s5
	s_mulk_i32 s4, 0x900
	s_add_u32 s4, s16, s4
	s_addc_u32 s5, s17, s7
	s_add_u32 s10, s4, s0
	s_addc_u32 s11, s5, s1
	s_cmp_eq_u32 s8, 0
	v_or_b32_e32 v0, v10, v126
	s_cselect_b32 s0, 2, 0
	v_lshl_add_u64 v[6:7], v[0:1], 1, s[2:3]
	v_lshl_add_u32 v0, s6, 4, v10
	s_cselect_b32 s1, 0x80, 0
	v_or_b32_e32 v0, v0, v126
	s_lshl_b32 s7, s0, 6
	v_lshl_add_u64 v[14:15], v[0:1], 1, s[2:3]
	v_add_u32_e32 v0, s7, v131
	s_waitcnt vmcnt(0)
	v_mad_u64_u32 v[18:19], s[2:3], v0, s6, v[128:129]
	v_add_u32_e32 v0, s7, v133
	v_mad_u64_u32 v[20:21], s[2:3], v0, s6, v[130:131]
	v_add_u32_e32 v0, s7, v202
	v_mov_b32_e32 v19, v1
	v_mov_b32_e32 v21, v1
	v_mul_lo_u32 v0, v0, s6
	v_lshl_add_u64 v[18:19], v[18:19], 1, s[10:11]
	v_lshl_add_u64 v[24:25], v[20:21], 1, s[10:11]
	v_or_b32_e32 v0, v0, v203
	global_load_dwordx4 v[2:5], v[6:7], off
	s_nop 0
	global_load_dwordx4 v[6:9], v[6:7], off offset:64
	s_nop 0
	global_load_dwordx4 v[10:13], v[14:15], off
	s_nop 0
	global_load_dwordx4 v[14:17], v[14:15], off offset:64
	s_nop 0
	global_load_dwordx4 v[20:23], v[18:19], off offset:768
	s_nop 0
	global_load_dwordx4 v[24:27], v[24:25], off offset:768
	v_lshl_add_u64 v[18:19], v[0:1], 1, s[10:11]
	v_add_u32_e32 v0, s7, v204
	v_mul_lo_u32 v0, v0, s6
	v_or_b32_e32 v0, v0, v203
	global_load_dwordx4 v[28:31], v[18:19], off offset:1536
	v_lshl_add_u64 v[18:19], v[0:1], 1, s[10:11]
	global_load_dwordx4 v[32:35], v[18:19], off offset:1536
	v_add_u32_e32 v0, s7, v108
	v_mul_lo_u32 v0, s6, v0
	v_or_b32_e32 v115, v203, v0
	v_add_u32_e32 v0, s7, v109
	v_mul_lo_u32 v0, s6, v0
	v_or_b32_e32 v116, v203, v0
	v_add_u32_e32 v0, s7, v110
	v_mad_u64_u32 v[90:91], s[4:5], s6, v0, v[86:87]
	v_add_u32_e32 v0, s7, v111
	s_lshl_b32 s3, s0, 8
	v_mad_u64_u32 v[92:93], s[4:5], s6, v0, v[88:89]
	v_mov_b32_e32 v0, v1
	s_waitcnt vmcnt(7)
	ds_write_b128 v129, v[2:5] offset:43072
	s_waitcnt vmcnt(6)
	ds_write_b128 v129, v[6:9] offset:44096
	s_waitcnt vmcnt(5)
	ds_write_b128 v129, v[10:13] offset:45120
	s_waitcnt vmcnt(4)
	ds_write_b128 v129, v[14:17] offset:46144
	v_mov_b32_e32 v2, v1
	v_mov_b32_e32 v3, v1
	v_mov_b64_e32 v[6:7], v[2:3]
	v_mov_b64_e32 v[10:11], v[2:3]
	v_mov_b64_e32 v[14:15], v[2:3]
	v_mov_b64_e32 v[18:19], v[2:3]
	v_mov_b64_e32 v[38:39], v[2:3]
	v_mov_b64_e32 v[42:43], v[2:3]
	v_mov_b64_e32 v[46:47], v[2:3]
	v_mov_b64_e32 v[50:51], v[2:3]
	s_mov_b32 s2, 0
	v_max_i32_e32 v112, s0, v87
	v_subrev_u32_e32 v113, s3, v105
	v_subrev_u32_e32 v114, s7, v107
	s_or_b32 s3, s7, 0xffffff40
	s_lshl_b32 s74, s6, 6
	v_writelane_b32 v255, s7, 1
	v_mov_b32_e32 v52, 0xf149f2ca
	s_mov_b32 s33, 0
	v_mov_b32_e32 v91, v132
	v_mov_b32_e32 v93, v106
	v_mov_b64_e32 v[4:5], v[0:1]
	v_mov_b64_e32 v[8:9], v[0:1]
	v_mov_b64_e32 v[12:13], v[0:1]
	v_mov_b64_e32 v[16:17], v[0:1]
	v_mov_b32_e32 v121, 0xf149f2ca
	v_mov_b64_e32 v[36:37], v[0:1]
	v_mov_b64_e32 v[40:41], v[0:1]
	v_mov_b64_e32 v[44:45], v[0:1]
	v_mov_b64_e32 v[48:49], v[0:1]
	v_mov_b32_e32 v119, 0
	v_mov_b32_e32 v118, 0xf149f2ca
	v_mov_b32_e32 v120, 0xf149f2ca
	v_readlane_b32 s13, v252, 26
	v_readlane_b32 s14, v252, 27
	v_readlane_b32 s15, v252, 28
	v_readlane_b32 s18, v252, 31
	v_readlane_b32 s19, v252, 32
	v_readlane_b32 s20, v252, 33
	v_readlane_b32 s21, v252, 34
	v_readlane_b32 s22, v252, 35
	v_readlane_b32 s23, v252, 36
	v_readlane_b32 s24, v252, 37
	v_readlane_b32 s25, v252, 38
	v_readlane_b32 s26, v252, 39
	v_readlane_b32 s27, v252, 40
	s_waitcnt lgkmcnt(0)
	s_barrier
	s_waitcnt vmcnt(3)
	ds_write_b128 v205, v[20:23]
	s_waitcnt vmcnt(2)
	ds_write_b128 v206, v[24:27]
	s_waitcnt vmcnt(1)
	ds_write_b16 v100, v28 offset:14336
	ds_write_b16_d16_hi v100, v28 offset:14496
	ds_write_b16 v100, v29 offset:14656
	ds_write_b16_d16_hi v100, v29 offset:14816
	ds_write_b16 v100, v30 offset:14976
	ds_write_b16_d16_hi v100, v30 offset:15136
	ds_write_b16 v100, v31 offset:15296
	ds_write_b16_d16_hi v100, v31 offset:15456
	s_waitcnt vmcnt(0)
	ds_write_b16 v101, v32 offset:14336
	ds_write_b16_d16_hi v101, v32 offset:14496
	ds_write_b16 v101, v33 offset:14656
	ds_write_b16_d16_hi v101, v33 offset:14816
	ds_write_b16 v101, v34 offset:14976
	ds_write_b16_d16_hi v101, v34 offset:15136
	ds_write_b16 v101, v35 offset:15296
	ds_write_b16_d16_hi v101, v35 offset:15456
	s_waitcnt lgkmcnt(0)
	s_barrier
	s_cmp_lg_u32 s3, s33
	s_cselect_b64 s[76:77], -1, 0
	s_cmp_eq_u32 s3, s33
	s_cbranch_scc1 .LBB0_601

; __device__ __forceinline__ f32x4 mfma16(bf16x8 a, bf16x8 b, f32x4 c) { return __builtin_amdgcn_mfma_f32_16x16x32_bf16(a, b, c, 0, 0, 0); }
; template <int DQK, int DV, int MODE> ...
;     ...
;     if (kt >= wkb && kt < wke) {
;       int path = 1; float cb = 0.f; bool need_mask = true;
;       if (MODE == 2) { need_mask = (kt * 64 + 63) > (qpos0 + w * 32); path = need_mask ? 1 : 0; }
;       if (MODE == 1) {
;         need_mask = (kt * 64 + 63) > (qpos0 + w * 32);
;         const int dmin = (qpos0 + w * 32) - (kt * 64 + 63);
;         if (dmin >= 0) {
;           const float blo = bias_lds[min(dmin, 2047)], bhi = bias_lds[min(dmin + 94, 2047)];
;           if (((__float_as_uint(blo) ^ __float_as_uint(bhi)) & 31u) == 0u) { path = 0; cb = blo; }
;         }
;       }
;       constexpr int QG = (DV == 128) ? ATT_QG_B : 2;
; #pragma unroll
;       for (int q0 = 0; q0 < 2; q0 += QG) {
;         f32x4 S[QG][4];
; #pragma unroll
;         for (int t = 0; t < 4; ++t) {
;           {
;             const bf16x8 kf = *(const bf16x8*)(Ks + (t * 16 + fr) * KST + fq * 8);
; #pragma unroll
;             for (int qq = 0; qq < QG; ++qq) S[qq][t] = __builtin_amdgcn_mfma_f32_16x16x32_bf16(kf, *(const bf16x8*)(Qs2 + ((q0 + qq) * NKS) * 512), (f32x4){0.f, 0.f, 0.f, 0.f}, 0, 0, 0);
;           }
; #pragma unroll
;           for (int ks = 1; ks < NKS; ++ks) {
;             const bf16x8 kf = *(const bf16x8*)(Ks + (t * 16 + fr) * KST + ks * 32 + fq * 8);
; #pragma unroll
;             for (int qq = 0; qq < QG; ++qq) S[qq][t] = mfma16(kf, *(const bf16x8*)(Qs2 + ((q0 + qq) * NKS + ks) * 512), S[qq][t]);
;           }
;         }
;     ...
;                 } else {
;                   const int rel = 128 + qrow - j;
;                   sx += bias_lds[min(max(rel, 0), 128)];
;                   if (rel < 0 || rel > 128 || j < jmin) sx = -1e30f;
;                 }
;                 P[t][r] = sx;
.LBB0_601:
	v_cmp_ge_u32_e32 vcc, s0, v112
	v_cmp_le_i32_e64 s[14:15], s0, v89
	v_mov_b64_e32 v[2:3], v[124:125]
	s_and_b64 s[4:5], vcc, s[14:15]
	s_and_saveexec_b64 s[78:79], s[4:5]
	s_cbranch_execz .LBB0_706
	ds_read_b128 v[68:71], v2
	ds_read_b128 v[136:139], v2 offset:1024
	ds_read_b128 v[94:97], v2 offset:2048
	ds_read_b128 v[140:143], v2 offset:3072
	ds_read_b128 v[52:55], v207
	ds_read_b128 v[60:63], v207 offset:64
	v_readlane_b32 s4, v255, 1
	s_waitcnt lgkmcnt(0)
	v_mfma_f32_16x16x32_bf16 v[56:59], v[52:55], v[68:71], 0
	ds_read_b128 v[144:147], v207 offset:5184
	v_mfma_f32_16x16x32_bf16 v[52:55], v[52:55], v[94:97], 0
	v_mfma_f32_16x16x32_bf16 v[64:67], v[60:63], v[140:143], v[52:55]
	v_mfma_f32_16x16x32_bf16 v[80:83], v[60:63], v[136:139], v[56:59]
	s_nop 5
	ds_read_b128 v[52:55], v207 offset:2560
	ds_read_b128 v[60:63], v207 offset:2624
	s_waitcnt lgkmcnt(1)
	v_mfma_f32_16x16x32_bf16 v[56:59], v[52:55], v[68:71], 0
	v_mfma_f32_16x16x32_bf16 v[52:55], v[52:55], v[94:97], 0
	s_waitcnt lgkmcnt(0)
	v_mfma_f32_16x16x32_bf16 v[76:79], v[60:63], v[136:139], v[56:59]
	v_mfma_f32_16x16x32_bf16 v[60:63], v[60:63], v[140:143], v[52:55]
	s_nop 4
	ds_read_b128 v[52:55], v207 offset:5120
	s_waitcnt lgkmcnt(0)
	v_mfma_f32_16x16x32_bf16 v[56:59], v[52:55], v[68:71], 0
	v_mfma_f32_16x16x32_bf16 v[52:55], v[52:55], v[94:97], 0
	v_mfma_f32_16x16x32_bf16 v[72:75], v[144:147], v[136:139], v[56:59]
	v_mfma_f32_16x16x32_bf16 v[56:59], v[144:147], v[140:143], v[52:55]
	s_nop 5
	ds_read_b128 v[52:55], v207 offset:7680
	s_waitcnt lgkmcnt(0)
	v_mfma_f32_16x16x32_bf16 v[68:71], v[52:55], v[68:71], 0
	v_mfma_f32_16x16x32_bf16 v[52:55], v[52:55], v[94:97], 0
	ds_read_b128 v[94:97], v207 offset:7744
	s_waitcnt lgkmcnt(0)
	v_mfma_f32_16x16x32_bf16 v[68:71], v[94:97], v[136:139], v[68:71]
	v_mfma_f32_16x16x32_bf16 v[52:55], v[94:97], v[140:143], v[52:55]
	v_add_u32_e32 v94, s4, v91
	s_branch .La_q1
	v_add_u32_e32 v136, s33, v114
	v_add_u32_e32 v0, 0x80, v136
	s_movk_i32 s4, 0x80
	v_cmp_lt_u32_e64 s[80:81], s4, v0
	s_movk_i32 s4, 0x81
	v_cmp_gt_u32_e32 vcc, s4, v0
	v_add_u32_e32 v0, v113, v93
	v_cmp_gt_u32_e64 s[38:39], s1, v94
	s_mov_b64 s[6:7], s[80:81]
	s_and_saveexec_b64 s[4:5], vcc
	s_cbranch_execz .LBB0_604
	ds_read_b32 v2, v0 offset:35328
	s_andn2_b64 s[6:7], s[80:81], exec
	s_and_b64 s[8:9], s[38:39], exec
	s_or_b64 s[6:7], s[6:7], s[8:9]
	s_waitcnt lgkmcnt(0)
	v_fmac_f32_e32 v2, 0x3e38aa3b, v80

; __device__ __forceinline__ unsigned pack2(float lo, float hi) { unsigned r; asm("v_cvt_pk_bf16_f32 %0, %1, %2" : "=v"(r) : "v"(lo), "v"(hi)); return r; }
; __device__ __forceinline__ float fexp2(float x) { return __builtin_amdgcn_exp2f(x); }
; __device__ __forceinline__ float fmax3(float a, float b, float c) { float r; asm("v_max3_f32 %0, %1, %2, %3" : "=v"(r) : "v"(a), "v"(b), "v"(c)); return r; }
; #define ATT_SCHED_BARRIER __builtin_amdgcn_sched_barrier(0)
; template <int DQK, int DV, int MODE> ...
;     ...
;                 } else {
;                   const int rel = 128 + qrow - j;
;                   sx += bias_lds[min(max(rel, 0), 128)];
;                   if (rel < 0 || rel > 128 || j < jmin) sx = -1e30f;
;                 }
;     ...
; #pragma unroll
;             for (int t = 0; t < 4; ++t) { mx = fmax3(mx, P[t][0], P[t][1]); mx = fmax3(mx, P[t][2], P[t][3]); }
;             mx = xmax_rows(mx);
;             mn = fmax3(mrow[qi], mx, mx);
; #pragma unroll
;             for (int t = 0; t < 4; ++t) P[t] = P[t] - mn;
;           }
;           {
;             const float alpha = fexp2(mrow[qi] - mn);
;             lrow[qi] *= alpha;
; #pragma unroll
;             for (int dt = 0; dt < NDT; ++dt) O[qi][dt] *= alpha;
;           }
;           mrow[qi] = mn;
;           f32x4 ls4 = (f32x4){0.f, 0.f, 0.f, 0.f};
; #pragma unroll
;           for (int t = 0; t < 4; ++t) {
; #pragma unroll
;             for (int r = 0; r < 4; ++r) P[t][r] = fexp2(P[t][r]);
;             ls4 += P[t];
;           }
;           lrow[qi] += (ls4[0] + ls4[1]) + (ls4[2] + ls4[3]);
; #pragma unroll
;           for (int s2 = 0; s2 < 2; ++s2) {
;             u32x4 pk;
;             pk.x = pack2(P[2 * s2][0], P[2 * s2][1]); pk.y = pack2(P[2 * s2][2], P[2 * s2][3]);
;             pk.z = pack2(P[2 * s2 + 1][0], P[2 * s2 + 1][1]); pk.w = pack2(P[2 * s2 + 1][2], P[2 * s2 + 1][3]);
;             pf[qq][s2] = __builtin_bit_cast(bf16x8, pk);
;           }
;           ATT_SCHED_BARRIER;
.La_q1_join:
	v_max3_f32 v71, v194, v2, v3
	s_nop 0
	v_max3_f32 v71, v71, v80, v81
	s_nop 0
	v_max3_f32 v71, v71, v82, v76
	s_nop 0
	v_max3_f32 v71, v71, v77, v78
	s_nop 0
	v_max3_f32 v71, v71, v79, v72
	s_nop 0
	v_max3_f32 v71, v71, v73, v74
	s_nop 0
	v_max3_f32 v71, v71, v75, v68
	s_nop 0
	v_max3_f32 v71, v71, v69, v70
	s_nop 0
	v_mov_b32_e32 v83, v71
	s_nop 1
	v_permlane16_swap_b32_e32 v71, v83
	v_max3_f32 v71, v71, v83, v83
	s_nop 0
	v_mov_b32_e32 v83, v71
	s_nop 1
	v_permlane32_swap_b32_e32 v71, v83
	v_max3_f32 v71, v71, v83, v83
	s_nop 0
	v_max3_f32 v121, v120, v71, v71
	s_nop 0
	v_sub_f32_e32 v71, v81, v121
	v_sub_f32_e32 v80, v80, v121
	v_sub_f32_e32 v3, v3, v121
	v_sub_f32_e32 v2, v2, v121
	v_sub_f32_e32 v81, v78, v121
	v_sub_f32_e32 v77, v77, v121
	v_sub_f32_e32 v76, v76, v121
	v_sub_f32_e32 v78, v82, v121
	v_sub_f32_e32 v74, v74, v121
	v_sub_f32_e32 v73, v73, v121
	v_sub_f32_e32 v72, v72, v121
	v_sub_f32_e32 v82, v79, v121
	v_sub_f32_e32 v70, v70, v121
	v_sub_f32_e32 v69, v69, v121
	v_sub_f32_e32 v68, v68, v121
	v_sub_f32_e32 v75, v75, v121
	v_exp_f32_e32 v98, v2
	v_exp_f32_e32 v99, v3
	v_exp_f32_e32 v94, v80
	v_exp_f32_e32 v95, v71
	v_exp_f32_e32 v78, v78
	v_exp_f32_e32 v79, v76
	v_exp_f32_e32 v96, v77
	v_exp_f32_e32 v97, v81
	v_exp_f32_e32 v82, v82
	v_exp_f32_e32 v83, v72
	v_exp_f32_e32 v76, v73
	v_exp_f32_e32 v77, v74
	v_exp_f32_e32 v2, v75
	v_exp_f32_e32 v3, v68
	v_exp_f32_e32 v80, v69
	v_exp_f32_e32 v81, v70
	v_cvt_pk_bf16_f32 v72, v98, v99
	v_cvt_pk_bf16_f32 v73, v94, v95
	v_cvt_pk_bf16_f32 v74, v78, v79
	v_cvt_pk_bf16_f32 v75, v96, v97
	v_cvt_pk_bf16_f32 v68, v82, v83
	v_cvt_pk_bf16_f32 v69, v76, v77
	v_cvt_pk_bf16_f32 v70, v2, v3
	v_cvt_pk_bf16_f32 v71, v80, v81
	s_branch .La_q2
	v_add_u32_e32 v137, 0x90, v136
	s_movk_i32 s72, 0x80
	v_cmp_lt_u32_e64 s[96:97], s72, v137
	s_movk_i32 s72, 0x81
	v_cmp_gt_u32_e64 s[72:73], s72, v137
	s_and_saveexec_b64 s[94:95], s[72:73]
	s_cbranch_execz .LBB0_668
	ds_read_b32 v137, v0 offset:35392
	s_andn2_b64 s[72:73], s[96:97], exec
	s_and_b64 s[38:39], s[38:39], exec
	s_or_b64 s[96:97], s[72:73], s[38:39]
	s_waitcnt lgkmcnt(0)
	v_fmac_f32_e32 v137, 0x3e38aa3b, v64

; __device__ __forceinline__ unsigned pack2(float lo, float hi) { unsigned r; asm("v_cvt_pk_bf16_f32 %0, %1, %2" : "=v"(r) : "v"(lo), "v"(hi)); return r; }
; __device__ __forceinline__ f32x4 mfma16(bf16x8 a, bf16x8 b, f32x4 c) { return __builtin_amdgcn_mfma_f32_16x16x32_bf16(a, b, c, 0, 0, 0); }
; __device__ __forceinline__ float fexp2(float x) { return __builtin_amdgcn_exp2f(x); }
; __device__ __forceinline__ float fmax3(float a, float b, float c) { float r; asm("v_max3_f32 %0, %1, %2, %3" : "=v"(r) : "v"(a), "v"(b), "v"(c)); return r; }
; #define ATT_SCHED_BARRIER __builtin_amdgcn_sched_barrier(0)
; template <int DQK, int DV, int MODE> ...
;     ...
; #pragma unroll
;             for (int t = 0; t < 4; ++t) { mx = fmax3(mx, P[t][0], P[t][1]); mx = fmax3(mx, P[t][2], P[t][3]); }
;             mx = xmax_rows(mx);
;             mn = fmax3(mrow[qi], mx, mx);
; #pragma unroll
;             for (int t = 0; t < 4; ++t) P[t] = P[t] - mn;
;           }
;           {
;             const float alpha = fexp2(mrow[qi] - mn);
;             lrow[qi] *= alpha;
; #pragma unroll
;             for (int dt = 0; dt < NDT; ++dt) O[qi][dt] *= alpha;
;           }
;           mrow[qi] = mn;
;           f32x4 ls4 = (f32x4){0.f, 0.f, 0.f, 0.f};
; #pragma unroll
;           for (int t = 0; t < 4; ++t) {
; #pragma unroll
;             for (int r = 0; r < 4; ++r) P[t][r] = fexp2(P[t][r]);
;             ls4 += P[t];
;           }
;           lrow[qi] += (ls4[0] + ls4[1]) + (ls4[2] + ls4[3]);
; #pragma unroll
;           for (int s2 = 0; s2 < 2; ++s2) {
;             u32x4 pk;
;             pk.x = pack2(P[2 * s2][0], P[2 * s2][1]); pk.y = pack2(P[2 * s2][2], P[2 * s2][3]);
;             pk.z = pack2(P[2 * s2 + 1][0], P[2 * s2 + 1][1]); pk.w = pack2(P[2 * s2 + 1][2], P[2 * s2 + 1][3]);
;             pf[qq][s2] = __builtin_bit_cast(bf16x8, pk);
;           }
;           ATT_SCHED_BARRIER;
;         }
; #pragma unroll
;         for (int s2 = 0; s2 < 2; ++s2)
; #pragma unroll
;           for (int dt = 0; dt < NDT; ++dt) {
;             const bf16x8 vf = *(const bf16x8*)(Vt + (dt * 16 + fr) * VTS + s2 * 32 + fq * 8);
; #pragma unroll
;             for (int qq = 0; qq < QG; ++qq) O[q0 + qq][dt] = mfma16(vf, pf[qq][s2], O[q0 + qq][dt]);
;             if ((dt & (ATT_PVB - 1)) == (ATT_PVB - 1)) ATT_SCHED_BARRIER;
;           }
.La_q2_join:
	v_pk_add_f32 v[98:99], v[98:99], 0 op_sel_hi:[1,0]
	v_pk_add_f32 v[94:95], v[94:95], 0 op_sel_hi:[1,0]
	v_sub_f32_e32 v0, v120, v121
	v_pk_add_f32 v[94:95], v[96:97], v[94:95]
	v_pk_add_f32 v[78:79], v[78:79], v[98:99]
	v_exp_f32_e32 v0, v0
	v_pk_add_f32 v[78:79], v[82:83], v[78:79]
	v_pk_add_f32 v[76:77], v[76:77], v[94:95]
	v_pk_add_f32 v[2:3], v[2:3], v[78:79]
	v_pk_add_f32 v[76:77], v[80:81], v[76:77]
	v_add_f32_e32 v2, v2, v3
	v_add_f32_e32 v3, v76, v77
	v_add_f32_e32 v82, v2, v3
	v_pk_mul_f32 v[50:51], v[50:51], v[0:1] op_sel_hi:[1,0]
	v_pk_mul_f32 v[48:49], v[48:49], v[0:1] op_sel_hi:[1,0]
	v_pk_mul_f32 v[46:47], v[46:47], v[0:1] op_sel_hi:[1,0]
	v_pk_mul_f32 v[44:45], v[44:45], v[0:1] op_sel_hi:[1,0]
	v_pk_mul_f32 v[42:43], v[42:43], v[0:1] op_sel_hi:[1,0]
	v_pk_mul_f32 v[40:41], v[40:41], v[0:1] op_sel_hi:[1,0]
	v_pk_mul_f32 v[38:39], v[38:39], v[0:1] op_sel_hi:[1,0]
	v_pk_mul_f32 v[36:37], v[36:37], v[0:1] op_sel_hi:[1,0]
	v_fmac_f32_e32 v82, v119, v0
	v_max3_f32 v0, v194, v137, v64
	s_nop 0
	v_max3_f32 v0, v0, v65, v66
	s_nop 0
	v_max3_f32 v0, v0, v67, v60
	s_nop 0
	v_max3_f32 v0, v0, v61, v62
	s_nop 0
	v_max3_f32 v0, v0, v63, v56
	s_nop 0
	v_max3_f32 v0, v0, v57, v58
	s_nop 0
	v_max3_f32 v0, v0, v59, v136
	s_nop 0
	v_max3_f32 v0, v0, v53, v54
	s_nop 0
	v_mov_b32_e32 v2, v0
	s_nop 1
	v_permlane16_swap_b32_e32 v0, v2
	v_max3_f32 v0, v0, v2, v2
	s_nop 0
	v_mov_b32_e32 v2, v0
	s_nop 1
	v_permlane32_swap_b32_e32 v0, v2
	v_max3_f32 v0, v0, v2, v2
	s_nop 0
	v_max3_f32 v52, v118, v0, v0
	s_nop 0
	v_sub_f32_e32 v55, v66, v52
	v_sub_f32_e32 v65, v65, v52
	v_sub_f32_e32 v3, v64, v52
	v_sub_f32_e32 v2, v137, v52
	v_sub_f32_e32 v62, v62, v52
	v_sub_f32_e32 v61, v61, v52
	v_sub_f32_e32 v64, v60, v52
	v_sub_f32_e32 v60, v67, v52
	v_sub_f32_e32 v66, v57, v52
	v_sub_f32_e32 v76, v56, v52
	v_exp_f32_e32 v2, v2
	v_exp_f32_e32 v3, v3
	v_exp_f32_e32 v56, v65
	v_exp_f32_e32 v57, v55
	v_sub_f32_e32 v67, v58, v52
	v_sub_f32_e32 v77, v63, v52
	v_sub_f32_e32 v78, v59, v52
	v_exp_f32_e32 v58, v60
	v_exp_f32_e32 v60, v61
	v_exp_f32_e32 v61, v62
	v_exp_f32_e32 v59, v64
	v_sub_f32_e32 v79, v54, v52
	v_sub_f32_e32 v53, v53, v52
	v_sub_f32_e32 v80, v136, v52
	v_exp_f32_e32 v64, v77
	v_exp_f32_e32 v65, v76
	v_exp_f32_e32 v66, v66
	v_exp_f32_e32 v67, v67
	v_exp_f32_e32 v76, v78
	v_exp_f32_e32 v78, v53
	v_exp_f32_e32 v79, v79
	v_exp_f32_e32 v77, v80
	v_pk_add_f32 v[54:55], v[2:3], 0 op_sel_hi:[1,0]
	v_pk_add_f32 v[62:63], v[56:57], 0 op_sel_hi:[1,0]
	v_sub_f32_e32 v0, v118, v52
	v_pk_add_f32 v[62:63], v[60:61], v[62:63]
	v_pk_add_f32 v[54:55], v[58:59], v[54:55]
	v_exp_f32_e32 v0, v0
	v_pk_add_f32 v[54:55], v[64:65], v[54:55]
	v_pk_add_f32 v[62:63], v[66:67], v[62:63]
	v_pk_add_f32 v[54:55], v[76:77], v[54:55]
	v_pk_add_f32 v[62:63], v[78:79], v[62:63]
	v_pk_mul_f32 v[18:19], v[18:19], v[0:1] op_sel_hi:[1,0]
	v_pk_mov_b32 v[80:81], v[54:55], v[62:63] op_sel:[1,0]
	v_mov_b32_e32 v55, v63
	v_pk_add_f32 v[54:55], v[80:81], v[54:55]
	v_pk_mul_f32 v[16:17], v[16:17], v[0:1] op_sel_hi:[1,0]
	v_pk_mul_f32 v[14:15], v[14:15], v[0:1] op_sel_hi:[1,0]
	v_pk_mul_f32 v[12:13], v[12:13], v[0:1] op_sel_hi:[1,0]
	v_pk_mul_f32 v[10:11], v[10:11], v[0:1] op_sel_hi:[1,0]
	v_pk_mul_f32 v[8:9], v[8:9], v[0:1] op_sel_hi:[1,0]
	v_pk_mul_f32 v[6:7], v[6:7], v[0:1] op_sel_hi:[1,0]
	v_pk_mul_f32 v[4:5], v[4:5], v[0:1] op_sel_hi:[1,0]
	v_add_f32_e32 v53, v54, v55
	v_fmac_f32_e32 v53, v117, v0
	v_cvt_pk_bf16_f32 v54, v2, v3
	v_cvt_pk_bf16_f32 v55, v56, v57
	v_cvt_pk_bf16_f32 v56, v58, v59
	v_cvt_pk_bf16_f32 v57, v60, v61
	v_cvt_pk_bf16_f32 v58, v64, v65
	v_cvt_pk_bf16_f32 v59, v66, v67
	v_cvt_pk_bf16_f32 v60, v76, v77
	v_cvt_pk_bf16_f32 v61, v78, v79
	ds_read_b128 v[62:65], v208 offset:14336
	s_waitcnt lgkmcnt(0)
	v_mfma_f32_16x16x32_bf16 v[48:51], v[62:65], v[72:75], v[48:51]
	v_mfma_f32_16x16x32_bf16 v[16:19], v[62:65], v[54:57], v[16:19]
	ds_read_b128 v[62:65], v208 offset:16896
	s_waitcnt lgkmcnt(0)
	v_mfma_f32_16x16x32_bf16 v[44:47], v[62:65], v[72:75], v[44:47]
	v_mfma_f32_16x16x32_bf16 v[12:15], v[62:65], v[54:57], v[12:15]
	ds_read_b128 v[62:65], v208 offset:19456
	s_waitcnt lgkmcnt(0)
	v_mfma_f32_16x16x32_bf16 v[40:43], v[62:65], v[72:75], v[40:43]
	v_mfma_f32_16x16x32_bf16 v[8:11], v[62:65], v[54:57], v[8:11]
	ds_read_b128 v[62:65], v208 offset:22016
	s_waitcnt lgkmcnt(0)
	v_mfma_f32_16x16x32_bf16 v[36:39], v[62:65], v[72:75], v[36:39]
	v_mfma_f32_16x16x32_bf16 v[2:5], v[62:65], v[54:57], v[4:7]
	ds_read_b128 v[54:57], v208 offset:14400
	s_waitcnt lgkmcnt(0)
	v_mfma_f32_16x16x32_bf16 v[48:51], v[54:57], v[68:71], v[48:51]
	v_mfma_f32_16x16x32_bf16 v[16:19], v[54:57], v[58:61], v[16:19]
	ds_read_b128 v[54:57], v208 offset:16960
	s_waitcnt lgkmcnt(0)
	v_mfma_f32_16x16x32_bf16 v[44:47], v[54:57], v[68:71], v[44:47]
	v_mfma_f32_16x16x32_bf16 v[12:15], v[54:57], v[58:61], v[12:15]
	ds_read_b128 v[54:57], v208 offset:19520
	s_waitcnt lgkmcnt(0)
	v_mfma_f32_16x16x32_bf16 v[40:43], v[54:57], v[68:71], v[40:43]
	v_mfma_f32_16x16x32_bf16 v[8:11], v[54:57], v[58:61], v[8:11]
	ds_read_b128 v[54:57], v208 offset:22080
	s_waitcnt lgkmcnt(0)
	v_mfma_f32_16x16x32_bf16 v[36:39], v[54:57], v[68:71], v[36:39]
	v_mfma_f32_16x16x32_bf16 v[4:7], v[54:57], v[58:61], v[2:5]
	v_mov_b32_e32 v120, v121
	v_mov_b32_e32 v118, v52
	v_mov_b32_e32 v119, v82
	v_mov_b32_e32 v117, v53

; template <int DQK, int DV, int MODE> ...
;     ...
;             for (int t = 0; t < 4; ++t)
; #pragma unroll
;               for (int r = 0; r < 4; ++r) {
;                 const int j = kt * 64 + t * 16 + fq * 4 + r;
;                 float sx = S[qq][t][r] * c1;
;                 if (MODE == 1) {
;                   const int dist = qpos0 + qrow - j;
;                   sx += bias_lds[min(max(dist, 0), 2047)];
;                   if (need_mask && dist < 0) sx = -1e30f;
;                 } else if (MODE == 2) {
;                   if ((qpos0 + qrow - j) < 0) sx = -1e30f;
;                 } else {
;                   const int rel = 128 + qrow - j;
;                   sx += bias_lds[min(max(rel, 0), 128)];
;                   if (rel < 0 || rel > 128 || j < jmin) sx = -1e30f;
;                 }
;                 P[t][r] = sx;
;               }
.La_q1:
	s_mov_b32 s4, 0x3e38aa3b
	v_add_u32_e32 v136, s33, v114
	v_add_u32_e32 v0, v113, v93
	v_add_u32_e32 v154, 0x8900, v0
	ds_read2_b32 v[156:157], v154 offset0:64 offset1:63
	ds_read2_b32 v[158:159], v154 offset0:62 offset1:61
	ds_read2_b32 v[160:161], v154 offset0:48 offset1:47
	ds_read2_b32 v[162:163], v154 offset0:46 offset1:45
	ds_read2_b32 v[164:165], v154 offset0:32 offset1:31
	ds_read2_b32 v[166:167], v154 offset0:30 offset1:29
	ds_read2_b32 v[168:169], v154 offset0:16 offset1:15
	ds_read2_b32 v[170:171], v154 offset0:14 offset1:13
	s_waitcnt lgkmcnt(7)
	v_fma_f32 v2, v80, s4, v156
	v_fma_f32 v3, v81, s4, v157
	s_waitcnt lgkmcnt(6)
	v_fma_f32 v80, v82, s4, v158
	v_fma_f32 v81, v83, s4, v159
	s_waitcnt lgkmcnt(5)
	v_fma_f32 v82, v76, s4, v160
	v_fma_f32 v76, v77, s4, v161
	s_waitcnt lgkmcnt(4)
	v_fma_f32 v77, v78, s4, v162
	v_fma_f32 v78, v79, s4, v163
	s_waitcnt lgkmcnt(3)
	v_fma_f32 v79, v72, s4, v164
	v_fma_f32 v72, v73, s4, v165
	s_waitcnt lgkmcnt(2)
	v_fma_f32 v73, v74, s4, v166
	v_fma_f32 v74, v75, s4, v167
	s_waitcnt lgkmcnt(1)
	v_fma_f32 v75, v68, s4, v168
	v_fma_f32 v68, v69, s4, v169
	s_waitcnt lgkmcnt(0)
	v_fma_f32 v69, v70, s4, v170
	v_fma_f32 v70, v71, s4, v171
	s_branch .La_q1_join
.La_q2:
	ds_read2_b32 v[156:157], v154 offset0:80 offset1:79
	ds_read2_b32 v[158:159], v154 offset0:78 offset1:77
	ds_read2_b32 v[160:161], v154 offset0:64 offset1:63
	ds_read2_b32 v[162:163], v154 offset0:62 offset1:61
	ds_read2_b32 v[164:165], v154 offset0:48 offset1:47
	ds_read2_b32 v[166:167], v154 offset0:46 offset1:45
	ds_read2_b32 v[168:169], v154 offset0:32 offset1:31
	ds_read2_b32 v[170:171], v154 offset0:30 offset1:29
	s_waitcnt lgkmcnt(7)
	v_fma_f32 v137, v64, s4, v156
	v_fma_f32 v64, v65, s4, v157
	s_waitcnt lgkmcnt(6)
	v_fma_f32 v65, v66, s4, v158
	v_fma_f32 v66, v67, s4, v159
	s_waitcnt lgkmcnt(5)
	v_fma_f32 v67, v60, s4, v160
	v_fma_f32 v60, v61, s4, v161
	s_waitcnt lgkmcnt(4)
	v_fma_f32 v61, v62, s4, v162
	v_fma_f32 v62, v63, s4, v163
	s_waitcnt lgkmcnt(3)
	v_fma_f32 v63, v56, s4, v164
	v_fma_f32 v56, v57, s4, v165
	s_waitcnt lgkmcnt(2)
	v_fma_f32 v57, v58, s4, v166
	v_fma_f32 v58, v59, s4, v167
	s_waitcnt lgkmcnt(1)
	v_fma_f32 v59, v52, s4, v168
	v_fma_f32 v136, v53, s4, v169
	s_waitcnt lgkmcnt(0)
	v_fma_f32 v53, v54, s4, v170
	v_fma_f32 v54, v55, s4, v171
	s_branch .La_q2_join
